# P8 idle workgroups run a hand-written per-wave copy engine (64 KiB per atomic grab, 16 loads in flight per lane, no polling)
# speedup vs baseline: 1.0067x; 1.0067x over previous
.LBB0_2096:
	s_cmp_lt_i32 s72, 9
	s_cselect_b64 s[0:1], -1, 0
	s_cmp_gt_i32 s73, 8
	s_cselect_b64 s[4:5], -1, 0
	s_and_b64 s[0:1], s[0:1], s[4:5]
	s_andn2_b64 vcc, exec, s[0:1]
	s_cbranch_vccnz .LBB0_2179
	s_and_b64 s[0:1], s[58:59], exec
	v_readlane_b32 s4, v242, 2
	s_cselect_b32 s33, 0xb0, s84
	v_mov_b32_e32 v149, 0
	v_readlane_b32 s5, v242, 3
	s_cmp_ge_i32 s92, s33
	v_readlane_b32 s6, v242, 4
	v_lshl_add_u64 v[128:129], s[4:5], 0, v[148:149]
	s_mov_b64 s[4:5], -1
	v_readlane_b32 s7, v242, 5
	s_cbranch_scc0 .LBB0_2131
	v_mbcnt_lo_u32_b32 v1, -1, 0
	v_mbcnt_hi_u32_b32 v1, -1, v1
	v_lshlrev_b32_e32 v104, 4, v1
	v_add_u32_e32 v105, 0x1000, v104
	v_readlane_b32 s20, v242, 43
	v_readlane_b32 s21, v242, 44
	v_readlane_b32 s22, v242, 2
	v_readlane_b32 s23, v242, 3
	v_mov_b32_e32 v2, 0
	v_mov_b32_e32 v3, 8
	s_mov_b32 s26, 0x10478000
	s_mov_b32 s27, 0x30478000
	s_mov_b64 s[24:25], exec
	s_mov_b64 exec, 1
	s_nop 4
	global_atomic_add v4, v2, v3, s[20:21] sc0
	s_mov_b64 exec, s[24:25]
	s_waitcnt vmcnt(0)
	v_readfirstlane_b32 s4, v4
	s_nop 3
.Lcp8_loop:
	s_cmp_ge_u32 s4, 0x1fe00
	s_cbranch_scc1 .Lcp8_done
	s_mov_b64 exec, 1
	global_atomic_add v4, v2, v3, s[20:21] sc0
	s_mov_b64 exec, s[24:25]
	s_mov_b32 s5, 0
.Lcp8_trip:
	s_add_i32 s6, s4, s5
	s_add_i32 s7, s6, 1
	s_cmp_ge_u32 s6, 0xff00
	s_cselect_b32 s8, s46, s44
	s_cselect_b32 s9, s47, s45
	s_cselect_b32 s19, s27, s26
	s_cselect_b32 s16, 0xff00, 0
	s_sub_u32 s16, s6, s16
	s_mul_hi_i32 s17, s16, 0x80808081
	s_add_i32 s17, s17, s16
	s_lshr_b32 s18, s17, 31
	s_ashr_i32 s17, s17, 8
	s_add_i32 s17, s17, s18
	s_mul_i32 s18, s17, 0x1fe
	s_sub_u32 s18, s16, s18
	s_lshl_b32 s17, s17, 22
	s_lshl_b32 s18, s18, 13
	s_add_u32 s17, s17, s18
	s_add_u32 s19, s19, s17
	s_add_u32 s17, s17, 0x4000
	s_add_u32 s8, s8, s17
	s_addc_u32 s9, s9, 0
	s_add_u32 s10, s22, s19
	s_addc_u32 s11, s23, 0
	s_cmp_ge_u32 s7, 0xff00
	s_cselect_b32 s12, s46, s44
	s_cselect_b32 s13, s47, s45
	s_cselect_b32 s19, s27, s26
	s_cselect_b32 s16, 0xff00, 0
	s_sub_u32 s16, s7, s16
	s_mul_hi_i32 s17, s16, 0x80808081
	s_add_i32 s17, s17, s16
	s_lshr_b32 s18, s17, 31
	s_ashr_i32 s17, s17, 8
	s_add_i32 s17, s17, s18
	s_mul_i32 s18, s17, 0x1fe
	s_sub_u32 s18, s16, s18
	s_lshl_b32 s17, s17, 22
	s_lshl_b32 s18, s18, 13
	s_add_u32 s17, s17, s18
	s_add_u32 s19, s19, s17
	s_add_u32 s17, s17, 0x4000
	s_add_u32 s12, s12, s17
	s_addc_u32 s13, s13, 0
	s_add_u32 s14, s22, s19
	s_addc_u32 s15, s23, 0
	global_load_dwordx4 v[40:43], v104, s[8:9] nt
	global_load_dwordx4 v[44:47], v104, s[8:9] offset:1024 nt
	global_load_dwordx4 v[48:51], v104, s[8:9] offset:2048 nt
	global_load_dwordx4 v[52:55], v104, s[8:9] offset:3072 nt
	global_load_dwordx4 v[56:59], v105, s[8:9] nt
	global_load_dwordx4 v[60:63], v105, s[8:9] offset:1024 nt
	global_load_dwordx4 v[64:67], v105, s[8:9] offset:2048 nt
	global_load_dwordx4 v[68:71], v105, s[8:9] offset:3072 nt
	global_load_dwordx4 v[72:75], v104, s[12:13] nt
	global_load_dwordx4 v[76:79], v104, s[12:13] offset:1024 nt
	global_load_dwordx4 v[80:83], v104, s[12:13] offset:2048 nt
	global_load_dwordx4 v[84:87], v104, s[12:13] offset:3072 nt
	global_load_dwordx4 v[88:91], v105, s[12:13] nt
	global_load_dwordx4 v[92:95], v105, s[12:13] offset:1024 nt
	global_load_dwordx4 v[96:99], v105, s[12:13] offset:2048 nt
	global_load_dwordx4 v[100:103], v105, s[12:13] offset:3072 nt
	s_waitcnt vmcnt(0)
	global_store_dwordx4 v104, v[40:43], s[10:11] nt
	global_store_dwordx4 v104, v[44:47], s[10:11] offset:1024 nt
	global_store_dwordx4 v104, v[48:51], s[10:11] offset:2048 nt
	global_store_dwordx4 v104, v[52:55], s[10:11] offset:3072 nt
	global_store_dwordx4 v105, v[56:59], s[10:11] nt
	global_store_dwordx4 v105, v[60:63], s[10:11] offset:1024 nt
	global_store_dwordx4 v105, v[64:67], s[10:11] offset:2048 nt
	global_store_dwordx4 v105, v[68:71], s[10:11] offset:3072 nt
	global_store_dwordx4 v104, v[72:75], s[14:15] nt
	global_store_dwordx4 v104, v[76:79], s[14:15] offset:1024 nt
	global_store_dwordx4 v104, v[80:83], s[14:15] offset:2048 nt
	global_store_dwordx4 v104, v[84:87], s[14:15] offset:3072 nt
	global_store_dwordx4 v105, v[88:91], s[14:15] nt
	global_store_dwordx4 v105, v[92:95], s[14:15] offset:1024 nt
	global_store_dwordx4 v105, v[96:99], s[14:15] offset:2048 nt
	global_store_dwordx4 v105, v[100:103], s[14:15] offset:3072 nt
	s_add_i32 s5, s5, 2
	s_cmp_lt_u32 s5, 8
	s_cbranch_scc1 .Lcp8_trip
	v_readfirstlane_b32 s4, v4
	s_nop 3
	s_branch .Lcp8_loop
.Lcp8_done:
.LBB0_2130:
	s_mov_b64 s[4:5], 0
